# GLU weight workspace stored fragment-major (P1 transposer writes it, P5 GLU loop reads it): each weight load reads one contiguous 1 KiB
# speedup vs baseline: 1.0168x; 1.0128x over previous
.LBB0_118:
	s_cmpk_gt_i32 s8, 0x11ff
	s_mov_b64 s[4:5], -1
	s_cbranch_scc0 .LBB0_124
	s_cmpk_gt_u32 s8, 0x19ff
	s_cbranch_scc0 .LBB0_121
	s_and_b32 s0, s14, 0x7fffffc0
	s_add_i32 s4, s0, 0xffff9800
	v_or_b32_e32 v4, s4, v25
	v_lshlrev_b64 v[2:3], 11, v[4:5]
	v_or_b32_e32 v4, s4, v26
	v_lshlrev_b64 v[18:19], 11, v[4:5]
	v_or_b32_e32 v4, s4, v27
	v_lshlrev_b64 v[20:21], 11, v[4:5]
	v_or_b32_e32 v4, s4, v28
	v_lshlrev_b64 v[22:23], 11, v[4:5]
	v_or_b32_e32 v4, s4, v29
	s_and_b32 s6, s10, 0x1e0
	v_lshlrev_b64 v[72:73], 11, v[4:5]
	v_or_b32_e32 v4, s4, v30
	s_lshl_b32 s0, s6, 2
	v_lshlrev_b64 v[74:75], 11, v[4:5]
	v_or_b32_e32 v4, s4, v32
	v_lshl_add_u64 v[0:1], v[14:15], 0, s[0:1]
	v_lshlrev_b64 v[76:77], 11, v[4:5]
	v_or_b32_e32 v4, s4, v33
	v_lshl_add_u64 v[2:3], v[0:1], 0, v[2:3]
	v_lshlrev_b64 v[78:79], 11, v[4:5]
	v_or_b32_e32 v4, s4, v34
	v_lshl_add_u64 v[18:19], v[0:1], 0, v[18:19]
	v_lshl_add_u64 v[20:21], v[0:1], 0, v[20:21]
	v_lshl_add_u64 v[22:23], v[0:1], 0, v[22:23]
	v_lshl_add_u64 v[72:73], v[0:1], 0, v[72:73]
	v_lshl_add_u64 v[74:75], v[0:1], 0, v[74:75]
	v_lshl_add_u64 v[76:77], v[0:1], 0, v[76:77]
	v_lshl_add_u64 v[78:79], v[0:1], 0, v[78:79]
	global_load_dword v67, v[2:3], off nt
	global_load_dword v80, v[18:19], off nt
	global_load_dword v81, v[20:21], off nt
	global_load_dword v82, v[22:23], off nt
	global_load_dword v83, v[72:73], off nt
	global_load_dword v84, v[74:75], off nt
	global_load_dword v85, v[76:77], off nt
	global_load_dword v86, v[78:79], off nt
	v_lshlrev_b64 v[2:3], 11, v[4:5]
	v_or_b32_e32 v4, s4, v35
	v_lshlrev_b64 v[18:19], 11, v[4:5]
	v_or_b32_e32 v4, s4, v36
	v_lshlrev_b64 v[20:21], 11, v[4:5]
	v_or_b32_e32 v4, s4, v38
	v_lshlrev_b64 v[22:23], 11, v[4:5]
	v_or_b32_e32 v4, s4, v39
	v_lshlrev_b64 v[72:73], 11, v[4:5]
	v_or_b32_e32 v4, s4, v40
	v_lshlrev_b64 v[74:75], 11, v[4:5]
	v_or_b32_e32 v4, s4, v41
	v_lshlrev_b64 v[76:77], 11, v[4:5]
	v_or_b32_e32 v4, s4, v42
	v_lshl_add_u64 v[2:3], v[0:1], 0, v[2:3]
	v_lshlrev_b64 v[78:79], 11, v[4:5]
	v_or_b32_e32 v4, s4, v44
	v_lshl_add_u64 v[18:19], v[0:1], 0, v[18:19]
	v_lshl_add_u64 v[20:21], v[0:1], 0, v[20:21]
	v_lshl_add_u64 v[22:23], v[0:1], 0, v[22:23]
	v_lshl_add_u64 v[72:73], v[0:1], 0, v[72:73]
	v_lshl_add_u64 v[74:75], v[0:1], 0, v[74:75]
	v_lshl_add_u64 v[76:77], v[0:1], 0, v[76:77]
	v_lshl_add_u64 v[78:79], v[0:1], 0, v[78:79]
	global_load_dword v87, v[2:3], off nt
	global_load_dword v88, v[18:19], off nt
	global_load_dword v89, v[20:21], off nt
	global_load_dword v90, v[22:23], off nt
	global_load_dword v91, v[72:73], off nt
	global_load_dword v92, v[74:75], off nt
	global_load_dword v93, v[76:77], off nt
	global_load_dword v94, v[78:79], off nt
	v_lshlrev_b64 v[2:3], 11, v[4:5]
	v_or_b32_e32 v4, s4, v45
	v_lshlrev_b64 v[18:19], 11, v[4:5]
	v_or_b32_e32 v4, s4, v46
	v_lshlrev_b64 v[20:21], 11, v[4:5]
	v_or_b32_e32 v4, s4, v47
	v_lshlrev_b64 v[22:23], 11, v[4:5]
	v_or_b32_e32 v4, s4, v48
	v_lshlrev_b64 v[72:73], 11, v[4:5]
	v_or_b32_e32 v4, s4, v50
	v_lshlrev_b64 v[74:75], 11, v[4:5]
	v_or_b32_e32 v4, s4, v51
	v_lshlrev_b64 v[76:77], 11, v[4:5]
	v_or_b32_e32 v4, s4, v52
	v_lshl_add_u64 v[2:3], v[0:1], 0, v[2:3]
	v_lshlrev_b64 v[78:79], 11, v[4:5]
	v_or_b32_e32 v4, s4, v53
	v_lshl_add_u64 v[18:19], v[0:1], 0, v[18:19]
	v_lshl_add_u64 v[20:21], v[0:1], 0, v[20:21]
	v_lshl_add_u64 v[22:23], v[0:1], 0, v[22:23]
	v_lshl_add_u64 v[72:73], v[0:1], 0, v[72:73]
	v_lshl_add_u64 v[74:75], v[0:1], 0, v[74:75]
	v_lshl_add_u64 v[76:77], v[0:1], 0, v[76:77]
	v_lshl_add_u64 v[78:79], v[0:1], 0, v[78:79]
	global_load_dword v95, v[2:3], off nt
	global_load_dword v96, v[18:19], off nt
	global_load_dword v97, v[20:21], off nt
	global_load_dword v98, v[22:23], off nt
	global_load_dword v99, v[72:73], off nt
	global_load_dword v100, v[74:75], off nt
	global_load_dword v101, v[76:77], off nt
	global_load_dword v102, v[78:79], off nt
	v_lshlrev_b64 v[2:3], 11, v[4:5]
	v_or_b32_e32 v4, s4, v54
	v_lshlrev_b64 v[18:19], 11, v[4:5]
	v_or_b32_e32 v4, s4, v55
	v_lshlrev_b64 v[20:21], 11, v[4:5]
	v_or_b32_e32 v4, s4, v56
	v_lshlrev_b64 v[22:23], 11, v[4:5]
	v_or_b32_e32 v4, s4, v57
	v_lshlrev_b64 v[72:73], 11, v[4:5]
	v_or_b32_e32 v4, s4, v58
	v_lshlrev_b64 v[74:75], 11, v[4:5]
	v_or_b32_e32 v4, s4, v59
	v_lshlrev_b64 v[76:77], 11, v[4:5]
	v_or_b32_e32 v4, s4, v60
	v_lshl_add_u64 v[2:3], v[0:1], 0, v[2:3]
	v_lshlrev_b64 v[78:79], 11, v[4:5]
	v_lshl_add_u64 v[18:19], v[0:1], 0, v[18:19]
	v_lshl_add_u64 v[20:21], v[0:1], 0, v[20:21]
	v_lshl_add_u64 v[22:23], v[0:1], 0, v[22:23]
	v_lshl_add_u64 v[72:73], v[0:1], 0, v[72:73]
	v_lshl_add_u64 v[74:75], v[0:1], 0, v[74:75]
	v_lshl_add_u64 v[76:77], v[0:1], 0, v[76:77]
	v_lshl_add_u64 v[0:1], v[0:1], 0, v[78:79]
	global_load_dword v4, v[2:3], off nt
	global_load_dword v78, v[18:19], off nt
	global_load_dword v79, v[20:21], off nt
	global_load_dword v103, v[22:23], off nt
	global_load_dword v104, v[72:73], off nt
	global_load_dword v105, v[74:75], off nt
	global_load_dword v106, v[76:77], off nt
	global_load_dword v107, v[0:1], off nt
	v_add_u32_e32 v0, 0x4000, v66
	s_waitcnt vmcnt(30)
	ds_write2_b32 v0, v67, v80 offset1:66
	s_waitcnt vmcnt(28)
	ds_write2_b32 v0, v81, v82 offset0:132 offset1:198
	s_waitcnt vmcnt(27)
	ds_write_b32 v66, v83 offset:17440
	v_add_u32_e32 v0, v24, v31
	v_add_u32_e32 v1, 0x4000, v0
	s_waitcnt vmcnt(25)
	ds_write2_b32 v1, v84, v85 offset1:66
	s_waitcnt vmcnt(23)
	ds_write2_b32 v1, v86, v87 offset0:132 offset1:198
	s_waitcnt vmcnt(22)
	ds_write_b32 v0, v88 offset:17440
	v_add_u32_e32 v0, v24, v37
	v_add_u32_e32 v1, 0x4000, v0
	s_waitcnt vmcnt(20)
	ds_write2_b32 v1, v89, v90 offset1:66
	s_waitcnt vmcnt(18)
	ds_write2_b32 v1, v91, v92 offset0:132 offset1:198
	s_waitcnt vmcnt(17)
	ds_write_b32 v0, v93 offset:17440
	v_add_u32_e32 v0, v24, v43
	v_add_u32_e32 v1, 0x4000, v0
	s_waitcnt vmcnt(15)
	ds_write2_b32 v1, v94, v95 offset1:66
	s_waitcnt vmcnt(13)
	ds_write2_b32 v1, v96, v97 offset0:132 offset1:198
	s_waitcnt vmcnt(12)
	ds_write_b32 v0, v98 offset:17440
	v_add_u32_e32 v0, v24, v49
	v_add_u32_e32 v1, 0x4000, v0
	s_waitcnt vmcnt(10)
	ds_write2_b32 v1, v99, v100 offset1:66
	s_waitcnt vmcnt(8)
	ds_write2_b32 v1, v101, v102 offset0:132 offset1:198
	v_add_u32_e32 v1, 0x4400, v0
	v_add_u32_e32 v0, 0x4800, v0
	s_waitcnt vmcnt(6)
	ds_write2_b32 v1, v4, v78 offset0:8 offset1:74
	s_waitcnt vmcnt(4)
	ds_write2_b32 v1, v79, v103 offset0:140 offset1:206
	s_waitcnt vmcnt(2)
	ds_write2_b32 v0, v104, v105 offset0:16 offset1:82
	s_waitcnt vmcnt(0)
	ds_write2_b32 v0, v106, v107 offset0:148 offset1:214
	s_waitcnt lgkmcnt(0)
	v_add_u32_e32 v67, 0x4000, v62
	ds_read2_b32 v[18:19], v67 offset0:33 offset1:41
	ds_read2_b32 v[20:21], v67 offset1:8
	ds_read2_b32 v[22:23], v67 offset0:66 offset1:74
	ds_read2_b32 v[72:73], v67 offset0:99 offset1:107
	ds_read2_b32 v[74:75], v67 offset0:132 offset1:140
	ds_read2_b32 v[76:77], v67 offset0:165 offset1:173
	ds_read2_b32 v[78:79], v67 offset0:198 offset1:206
	ds_read2_b32 v[80:81], v67 offset0:231 offset1:239
	s_mov_b32 s5, s1
	v_or_b32_e32 v4, s6, v61
	v_lshl_add_u64 v[82:83], s[4:5], 1, v[8:9]
	s_lshl_b32 s100, s4, 6
	s_lshl_b32 s101, s6, 10
	s_add_u32 s100, s100, s101
	s_add_u32 s100, s100, 0x1a00000
	s_add_u32 s100, s62, s100
	s_addc_u32 s101, s63, 0
	v_and_b32_e32 v86, 7, v144
	v_lshlrev_b32_e32 v86, 9, v86
	v_lshl_add_u32 v86, v61, 4, v86
	v_lshlrev_b32_e32 v4, 10, v4
	s_waitcnt lgkmcnt(6)
	v_cvt_pk_bf16_f32 v0, v20, v18
	s_waitcnt lgkmcnt(4)
	v_cvt_pk_bf16_f32 v1, v22, v72
	s_waitcnt lgkmcnt(2)
	v_cvt_pk_bf16_f32 v2, v74, v76
	s_waitcnt lgkmcnt(0)
	v_cvt_pk_bf16_f32 v3, v78, v80
	v_lshl_add_u64 v[84:85], v[82:83], 0, v[4:5]
	global_store_dwordx4 v86, v[0:3], s[100:101]
	v_or_b32_e32 v4, s6, v63
	v_lshlrev_b32_e32 v4, 10, v4
	v_cvt_pk_bf16_f32 v0, v21, v19
	v_cvt_pk_bf16_f32 v1, v23, v73
	v_cvt_pk_bf16_f32 v2, v75, v77
	v_cvt_pk_bf16_f32 v3, v79, v81
	ds_read2_b32 v[20:21], v67 offset0:49 offset1:57
	ds_read2_b32 v[22:23], v67 offset0:16 offset1:24
	ds_read2_b32 v[72:73], v67 offset0:82 offset1:90
	ds_read2_b32 v[74:75], v67 offset0:115 offset1:123
	ds_read2_b32 v[76:77], v67 offset0:148 offset1:156
	ds_read2_b32 v[78:79], v67 offset0:181 offset1:189
	ds_read2_b32 v[80:81], v67 offset0:214 offset1:222
	ds_read2_b32 v[84:85], v67 offset0:247 offset1:255
	v_lshl_add_u64 v[18:19], v[82:83], 0, v[4:5]
	v_or_b32_e32 v4, s6, v64
	v_lshlrev_b32_e32 v4, 10, v4
	global_store_dwordx4 v86, v[0:3], s[100:101] offset:128
	v_lshl_add_u64 v[18:19], v[82:83], 0, v[4:5]
	v_or_b32_e32 v4, s6, v65
	s_waitcnt lgkmcnt(6)
	v_cvt_pk_bf16_f32 v0, v22, v20
	s_waitcnt lgkmcnt(4)
	v_cvt_pk_bf16_f32 v1, v72, v74
	s_waitcnt lgkmcnt(2)
	v_cvt_pk_bf16_f32 v2, v76, v78
	s_waitcnt lgkmcnt(0)
	v_cvt_pk_bf16_f32 v3, v80, v84
	v_lshlrev_b32_e32 v4, 10, v4
	global_store_dwordx4 v86, v[0:3], s[100:101] offset:256
	v_lshl_add_u64 v[18:19], v[82:83], 0, v[4:5]
	s_mov_b64 s[4:5], 0
	v_cvt_pk_bf16_f32 v0, v23, v21
	v_cvt_pk_bf16_f32 v1, v73, v75
	v_cvt_pk_bf16_f32 v2, v77, v79
	v_cvt_pk_bf16_f32 v3, v81, v85
	global_store_dwordx4 v86, v[0:3], s[100:101] offset:384
	s_waitcnt lgkmcnt(0)

.LBB0_448:
	s_cmp_lt_i32 s80, 6
	s_cselect_b64 s[0:1], -1, 0
	s_cmp_gt_i32 s81, 5
	s_cselect_b64 s[4:5], -1, 0
	s_and_b64 s[0:1], s[0:1], s[4:5]
	s_andn2_b64 vcc, exec, s[0:1]
	s_cbranch_vccnz .LBB0_522
	s_cmpk_gt_i32 s2, 0x1ff
	s_cbranch_scc1 .LBB0_468
	v_lshrrev_b32_e32 v4, 5, v193
	v_mov_b32_e32 v139, 0
	v_and_b32_e32 v136, 31, v144
	v_lshlrev_b32_e32 v140, 4, v4
	v_mov_b32_e32 v141, v139
	v_lshl_or_b32 v138, s3, 7, v136
	v_lshl_add_u64 v[0:1], s[62:63], 0, v[140:141]
	s_mov_b64 s[4:5], 0x1c30000
	s_add_u32 s10, s62, 0xc000000
	v_lshl_add_u64 v[142:143], v[0:1], 0, s[4:5]
	v_lshlrev_b64 v[0:1], 5, v[138:139]
	s_addc_u32 s11, s63, 0
	v_lshl_add_u64 v[148:149], v[142:143], 0, v[0:1]
	v_or_b32_e32 v0, 32, v138
	v_mov_b32_e32 v1, v139
	s_add_u32 s0, s62, 0x1c50000
	v_lshlrev_b64 v[0:1], 5, v[0:1]
	s_addc_u32 s1, s63, 0
	v_lshl_add_u64 v[150:151], v[142:143], 0, v[0:1]
	v_or_b32_e32 v0, 64, v138
	v_mov_b32_e32 v1, v139
	v_lshlrev_b64 v[0:1], 5, v[0:1]
	v_or_b32_e32 v138, 0x60, v138
	s_waitcnt lgkmcnt(0)
	s_add_u32 s14, s62, 0x1c20000
	v_lshl_add_u64 v[152:153], v[142:143], 0, v[0:1]
	v_lshlrev_b64 v[0:1], 5, v[138:139]
	s_addc_u32 s15, s63, 0
	s_andn2_b32 s91, s91, 63
	v_lshl_add_u64 v[154:155], v[142:143], 0, v[0:1]
	v_or_b32_e32 v0, s91, v193
	v_ashrrev_i32_e32 v1, 31, v0
	v_lshlrev_b32_e32 v138, 3, v193
	v_and_b32_e32 v137, 15, v144
	v_lshl_add_u64 v[156:157], v[0:1], 3, s[14:15]
	v_lshl_add_u64 v[0:1], s[62:63], 0, v[138:139]
	s_mov_b64 s[4:5], 0x2a00000
	v_lshl_add_u64 v[158:159], v[0:1], 0, s[4:5]
	s_lshl_b32 s4, s3, 6
	v_lshl_or_b32 v0, s3, 4, v137
	v_mov_b32_e32 v1, v139
	s_mul_i32 s6, s3, 0x2200
	s_add_u32 s4, s48, s4
	v_lshlrev_b64 v[0:1], 8, v[0:1]
	s_addc_u32 s5, s49, 0
	v_and_b32_e32 v138, 48, v193
	v_lshl_add_u64 v[0:1], s[0:1], 0, v[0:1]
	s_add_i32 s6, s6, 0
	v_lshl_add_u64 v[160:161], s[4:5], 0, v[138:139]
	v_lshl_add_u64 v[162:163], v[0:1], 0, v[138:139]
	s_movk_i32 s5, 0x110
	v_mov_b32_e32 v0, s6
	v_mad_u32_u24 v7, v136, s5, v0
	v_and_b32_e32 v0, 48, v144
	v_add_u32_e32 v9, s6, v0
	v_or_b32_e32 v0, s91, v136
	v_lshrrev_b32_e32 v2, 1, v193
	v_ashrrev_i32_e32 v1, 31, v0
	v_and_b32_e32 v2, 24, v2
	s_add_i32 s4, 0, 0x11000
	v_lshlrev_b64 v[0:1], 10, v[0:1]
	v_add_u32_e32 v147, s4, v2
	v_lshl_add_u64 v[2:3], s[62:63], 0, v[0:1]
	v_lshl_add_u64 v[164:165], s[0:1], 0, v[138:139]
	v_lshl_add_u64 v[2:3], v[2:3], 0, v[140:141]
	s_lshl_b32 s0, s91, 10
	v_lshl_add_u32 v2, v193, 4, s0
	v_mov_b32_e32 v3, 0
	v_lshl_add_u64 v[2:3], s[62:63], 0, v[2:3]
	s_mov_b64 s[0:1], 0x1a00000
	v_lshl_add_u64 v[168:169], v[2:3], 0, s[0:1]
	s_mov_b64 s[0:1], 0x1a08000
	v_lshl_add_u64 v[170:171], v[2:3], 0, s[0:1]
	s_mov_b64 s[0:1], 0x1a08400
	v_lshl_add_u64 v[172:173], v[2:3], 0, s[0:1]
	s_mov_b64 s[0:1], 0x1a08800
	v_lshl_add_u64 v[174:175], v[2:3], 0, s[0:1]
	s_mov_b64 s[0:1], 0x1a08c00
	v_lshlrev_b32_e32 v6, 3, v4
	v_lshl_add_u64 v[176:177], v[2:3], 0, s[0:1]
	v_or_b32_e32 v2, 32, v193
	v_lshl_or_b32 v4, v4, 2, s91
	v_mul_u32_u24_e32 v3, 0x410, v136
	v_mul_u32_u24_e32 v11, 0x410, v2
	v_lshlrev_b32_e32 v12, 1, v4
	v_add3_u32 v141, s4, v3, v12
	v_add3_u32 v183, s4, v11, v12
	v_lshlrev_b32_e32 v12, 3, v144
	v_and_b32_e32 v180, 0x1f8, v12
	v_add_u32_e32 v12, 0x200, v144
	v_lshrrev_b32_e32 v184, 6, v12
	v_add_u32_e32 v12, 0x600, v144
	s_add_i32 s5, 0, 0x21400
	s_lshl_b32 s7, s91, 2
	v_lshrrev_b32_e32 v188, 6, v12
	v_add_u32_e32 v12, 0xa00, v144
	s_add_i32 s7, s5, s7
	v_ashrrev_i32_e32 v5, 31, v4
	v_lshlrev_b32_e32 v3, 2, v136
	v_lshlrev_b32_e32 v11, 2, v2
	v_lshrrev_b32_e32 v192, 6, v12
	v_add_u32_e32 v12, 0xe00, v144
	v_or_b32_e32 v0, v0, v140
	v_add_u32_e32 v145, s4, v140
	v_lshlrev_b64 v[4:5], 2, v[4:5]
	v_add_u32_e32 v181, s7, v3
	v_lshrrev_b32_e32 v182, 6, v144
	v_lshrrev_b32_e32 v196, 6, v12
	v_add_u32_e32 v187, s5, v3
	v_add_u32_e32 v189, s5, v11
	v_lshl_add_u32 v3, v180, 1, s4
	v_lshl_add_u64 v[0:1], s[62:63], 0, v[0:1]
	s_mov_b64 s[4:5], 0x1a08160
	v_lshlrev_b32_e32 v8, 2, v193
	v_mul_u32_u24_e32 v10, 0x110, v137
	s_movk_i32 s17, 0x410
	v_lshl_add_u64 v[178:179], s[52:53], 0, v[4:5]
	v_add_u32_e32 v185, s7, v11
	s_add_u32 s19, s62, 0x1d00000
	v_lshl_add_u64 v[198:199], s[54:55], 0, v[4:5]
	v_mul_u32_u24_e32 v4, 0x410, v182
	v_mul_u32_u24_e32 v5, 0x410, v184
	v_mul_u32_u24_e32 v11, 0x410, v188
	v_mul_u32_u24_e32 v12, 0x410, v192
	v_mul_u32_u24_e32 v13, 0x410, v196
	v_lshl_add_u64 v[200:201], v[0:1], 0, s[4:5]
	s_mov_b64 s[100:101], 0xa000
	v_lshl_add_u64 v[200:201], v[168:169], 0, s[100:101]
	v_mbcnt_lo_u32_b32 v0, -1, 0
	s_mov_b32 s34, 0x3a2aaaab
	s_mov_b32 s13, 0
	v_lshl_add_u64 v[166:167], s[48:49], 0, v[138:139]
	v_cmp_gt_u32_e64 s[0:1], 32, v193
	v_or_b32_e32 v186, 16, v182
	v_or_b32_e32 v190, 32, v182
	v_or_b32_e32 v194, 48, v182
	v_mov_b32_e32 v197, v139
	s_addc_u32 s21, s63, 0
	v_mad_u32_u24 v191, v2, s17, 0
	v_mad_u32_u24 v195, v136, s17, 0
	v_add_u32_e32 v220, v7, v6
	v_add_u32_e32 v221, s6, v8
	v_add_u32_e32 v222, v9, v10
	s_mov_b32 s16, 0x3e6d3388
	s_mov_b32 s18, 0x3f07dc22
	s_mov_b32 s20, 0xbf3a00e3
	s_mov_b32 s22, 0x3f35f0e3
	s_mov_b32 s24, 0xbe11a98e
	s_mov_b32 s26, 0x3e027906
	s_mov_b32 s28, 0xbf38aa3b
	s_movk_i32 s23, 0x8000
	s_mov_b64 s[30:31], 0x2000
	v_mbcnt_hi_u32_b32 v223, -1, v0
	s_movk_i32 s25, 0x2400
	s_movk_i32 s27, 0x2000
	v_lshlrev_b32_e32 v202, 2, v136
	s_mov_b32 s29, 0x20000
	s_mov_b32 s37, 0x40000
	s_mov_b32 s35, 0x3b000000
	s_mov_b32 s36, 0x3727c5ac
	s_mov_b32 s50, 0xf800000
	v_mov_b32_e32 v224, 0x260
	v_lshlrev_b32_e32 v204, 2, v2
	s_brev_b32 s51, 32
	s_movk_i32 s52, 0x1000
	v_mov_b32_e32 v225, 0x2400
	v_add_u32_e32 v226, v3, v4
	v_add_u32_e32 v227, v3, v5
	v_add_u32_e32 v228, v3, v11
	v_add_u32_e32 v229, v3, v12
	v_add_u32_e32 v230, v3, v13
	s_mov_b32 s38, s2
	s_branch .LBB0_452

.LBB0_456:
	v_or_b32_e32 v0, s12, v136
	v_mad_u32_u24 v0, v0, s17, v138
	ds_read_b128 v[48:51], v0
	v_add_u32_e32 v205, 0x400, v221
	v_add_u32_e32 v231, 0x800, v221
	v_add_u32_e32 v234, 0xc00, v221
	v_add_u32_e32 v235, 0x1000, v221
	s_waitcnt lgkmcnt(0)
	v_mfma_f32_32x32x16_bf16 v[0:15], v[64:67], v[48:51], 0
	v_add_u32_e32 v236, 0x1200, v221
	v_add_u32_e32 v237, 0x1400, v221
	v_add_u32_e32 v238, 0x1600, v221
	v_add_u32_e32 v239, 0x1800, v221
	v_add_u32_e32 v240, 0x1a00, v221
	v_add_u32_e32 v241, 0x1c00, v221
	v_add_u32_e32 v242, 0x1e00, v221
	v_mfma_f32_32x32x16_bf16 v[16:31], v[68:71], v[48:51], 0
	s_nop 3
	v_cvt_pk_bf16_f32 v0, v0, v1
	v_cvt_pk_bf16_f32 v1, v2, v3
	v_cvt_pk_bf16_f32 v2, v4, v5
	v_cvt_pk_bf16_f32 v3, v6, v7
	v_cvt_pk_bf16_f32 v4, v8, v9
	v_cvt_pk_bf16_f32 v5, v10, v11
	v_cvt_pk_bf16_f32 v6, v12, v13
	v_mfma_f32_32x32x16_bf16 v[32:47], v[72:75], v[48:51], 0
	v_cvt_pk_bf16_f32 v7, v14, v15
	v_cvt_pk_bf16_f32 v8, v16, v17
	v_cvt_pk_bf16_f32 v9, v18, v19
	v_cvt_pk_bf16_f32 v10, v20, v21
	v_cvt_pk_bf16_f32 v11, v22, v23
	v_cvt_pk_bf16_f32 v12, v24, v25
	v_cvt_pk_bf16_f32 v13, v26, v27
	v_mfma_f32_32x32x16_bf16 v[48:63], v[76:79], v[48:51], 0
	v_cvt_pk_bf16_f32 v14, v28, v29
	v_cvt_pk_bf16_f32 v15, v30, v31
	s_nop 1
	v_cvt_pk_bf16_f32 v16, v32, v33
	v_cvt_pk_bf16_f32 v17, v34, v35
	v_cvt_pk_bf16_f32 v18, v36, v37
	v_cvt_pk_bf16_f32 v19, v38, v39
	v_cvt_pk_bf16_f32 v20, v40, v41
	v_cvt_pk_bf16_f32 v21, v42, v43
	v_cvt_pk_bf16_f32 v22, v44, v45
	v_cvt_pk_bf16_f32 v23, v46, v47
	v_cvt_pk_bf16_f32 v24, v48, v49
	v_cvt_pk_bf16_f32 v25, v50, v51
	v_cvt_pk_bf16_f32 v26, v52, v53
	v_cvt_pk_bf16_f32 v27, v54, v55
	v_cvt_pk_bf16_f32 v28, v56, v57
	v_cvt_pk_bf16_f32 v29, v58, v59
	v_cvt_pk_bf16_f32 v30, v60, v61
	v_cvt_pk_bf16_f32 v31, v62, v63
	ds_write2_b64 v220, v[0:1], v[2:3] offset1:2
	ds_write2_b64 v220, v[4:5], v[6:7] offset0:4 offset1:6
	ds_write2_b64 v220, v[8:9], v[10:11] offset0:8 offset1:10
	ds_write2_b64 v220, v[12:13], v[14:15] offset0:12 offset1:14
	ds_write2_b64 v220, v[16:17], v[18:19] offset0:16 offset1:18
	ds_write2_b64 v220, v[20:21], v[22:23] offset0:20 offset1:22
	ds_write2_b64 v220, v[24:25], v[26:27] offset0:24 offset1:26
	ds_write2_b64 v220, v[28:29], v[30:31] offset0:28 offset1:30
	s_waitcnt lgkmcnt(0)
	ds_read2_b32 v[0:1], v221 offset1:68
	ds_read2_b32 v[2:3], v221 offset0:136 offset1:204
	ds_read2_b32 v[4:5], v205 offset0:16 offset1:84
	ds_read2_b32 v[6:7], v205 offset0:152 offset1:220
	ds_read2_b32 v[8:9], v231 offset0:32 offset1:100
	ds_read2_b32 v[10:11], v231 offset0:168 offset1:236
	ds_read2_b32 v[12:13], v234 offset0:48 offset1:116
	ds_read2_b32 v[14:15], v234 offset0:184 offset1:252
	ds_read2_b32 v[16:17], v235 offset0:64 offset1:132
	ds_read2_b32 v[18:19], v236 offset0:72 offset1:140
	ds_read2_b32 v[20:21], v237 offset0:80 offset1:148
	ds_read2_b32 v[22:23], v238 offset0:88 offset1:156
	ds_read2_b32 v[24:25], v239 offset0:96 offset1:164
	ds_read2_b32 v[26:27], v240 offset0:104 offset1:172
	ds_read2_b32 v[28:29], v241 offset0:112 offset1:180
	ds_read2_b32 v[30:31], v242 offset0:120 offset1:188
	s_waitcnt lgkmcnt(14)
	v_lshlrev_b32_e32 v32, 16, v0
	v_and_b32_e32 v33, 0xffff0000, v0
	s_waitcnt lgkmcnt(5)
	v_lshlrev_b32_e32 v52, 16, v20
	v_and_b32_e32 v53, 0xffff0000, v20
	v_lshlrev_b32_e32 v55, 16, v21
	v_and_b32_e32 v54, 0xffff0000, v21
	s_waitcnt lgkmcnt(4)
	v_lshlrev_b32_e32 v20, 16, v22
	v_and_b32_e32 v21, 0xffff0000, v22
	v_lshlrev_b32_e32 v57, 16, v23
	v_and_b32_e32 v56, 0xffff0000, v23
	s_waitcnt lgkmcnt(3)
	v_lshlrev_b32_e32 v23, 16, v24
	v_and_b32_e32 v22, 0xffff0000, v24
	v_lshlrev_b32_e32 v59, 16, v25
	v_and_b32_e32 v58, 0xffff0000, v25
	s_waitcnt lgkmcnt(2)
	v_lshlrev_b32_e32 v25, 16, v26
	v_and_b32_e32 v24, 0xffff0000, v26
	v_lshlrev_b32_e32 v61, 16, v27
	v_and_b32_e32 v60, 0xffff0000, v27
	s_waitcnt lgkmcnt(1)
	v_lshlrev_b32_e32 v27, 16, v28
	v_and_b32_e32 v26, 0xffff0000, v28
	v_lshlrev_b32_e32 v63, 16, v29
	v_and_b32_e32 v62, 0xffff0000, v29
	s_waitcnt lgkmcnt(0)
	v_lshlrev_b32_e32 v29, 16, v30
	v_and_b32_e32 v28, 0xffff0000, v30
	v_lshlrev_b32_e32 v233, 16, v31
	v_and_b32_e32 v232, 0xffff0000, v31
	v_pk_fma_f32 v[30:31], v[206:207], v[216:217], v[32:33]
	v_lshlrev_b32_e32 v0, 16, v1
	v_and_b32_e32 v1, 0xffff0000, v1
	v_pk_fma_f32 v[30:31], v[214:215], v[216:217], v[30:31] op_sel:[0,1,0] op_sel_hi:[1,0,1]
	v_lshlrev_b32_e32 v34, 16, v2
	v_pk_fma_f32 v[0:1], v[206:207], v[30:31], v[0:1] op_sel:[0,1,0] op_sel_hi:[1,0,1]
	v_and_b32_e32 v35, 0xffff0000, v2
	v_pk_fma_f32 v[0:1], v[214:215], v[30:31], v[0:1]
	v_cvt_pk_bf16_f32 v32, v30, v31
	v_pk_fma_f32 v[30:31], v[206:207], v[0:1], v[34:35] op_sel:[0,1,0] op_sel_hi:[1,0,1]
	v_lshlrev_b32_e32 v2, 16, v3
	v_and_b32_e32 v3, 0xffff0000, v3
	v_cvt_pk_bf16_f32 v33, v0, v1
	v_pk_fma_f32 v[0:1], v[214:215], v[0:1], v[30:31]
	v_lshlrev_b32_e32 v36, 16, v4
	v_pk_fma_f32 v[2:3], v[206:207], v[0:1], v[2:3] op_sel:[0,1,0] op_sel_hi:[1,0,1]
	v_and_b32_e32 v37, 0xffff0000, v4
	v_cvt_pk_bf16_f32 v30, v0, v1
	v_pk_fma_f32 v[0:1], v[214:215], v[0:1], v[2:3]
	v_lshlrev_b32_e32 v4, 16, v5
	v_pk_fma_f32 v[2:3], v[206:207], v[0:1], v[36:37] op_sel:[0,1,0] op_sel_hi:[1,0,1]
	v_and_b32_e32 v5, 0xffff0000, v5
	v_cvt_pk_bf16_f32 v31, v0, v1
	v_pk_fma_f32 v[0:1], v[214:215], v[0:1], v[2:3]
	v_lshlrev_b32_e32 v38, 16, v6
	v_pk_fma_f32 v[2:3], v[206:207], v[0:1], v[4:5] op_sel:[0,1,0] op_sel_hi:[1,0,1]
	v_and_b32_e32 v39, 0xffff0000, v6
	ds_write2_b32 v221, v30, v31 offset0:136 offset1:204
	v_cvt_pk_bf16_f32 v30, v0, v1
	v_pk_fma_f32 v[0:1], v[214:215], v[0:1], v[2:3]
	v_lshlrev_b32_e32 v6, 16, v7
	v_pk_fma_f32 v[2:3], v[206:207], v[0:1], v[38:39] op_sel:[0,1,0] op_sel_hi:[1,0,1]
	v_and_b32_e32 v7, 0xffff0000, v7
	v_cvt_pk_bf16_f32 v4, v0, v1
	v_pk_fma_f32 v[0:1], v[214:215], v[0:1], v[2:3]
	v_lshlrev_b32_e32 v40, 16, v8
	v_pk_fma_f32 v[2:3], v[206:207], v[0:1], v[6:7] op_sel:[0,1,0] op_sel_hi:[1,0,1]
	v_and_b32_e32 v41, 0xffff0000, v8
	ds_write2_b32 v205, v30, v4 offset0:16 offset1:84
	v_cvt_pk_bf16_f32 v4, v0, v1
	v_pk_fma_f32 v[0:1], v[214:215], v[0:1], v[2:3]
	v_lshlrev_b32_e32 v8, 16, v9
	v_pk_fma_f32 v[2:3], v[206:207], v[0:1], v[40:41] op_sel:[0,1,0] op_sel_hi:[1,0,1]
	v_and_b32_e32 v9, 0xffff0000, v9
	v_cvt_pk_bf16_f32 v5, v0, v1
	v_pk_fma_f32 v[0:1], v[214:215], v[0:1], v[2:3]
	v_lshlrev_b32_e32 v42, 16, v10
	v_pk_fma_f32 v[2:3], v[206:207], v[0:1], v[8:9] op_sel:[0,1,0] op_sel_hi:[1,0,1]
	v_and_b32_e32 v43, 0xffff0000, v10
	ds_write2_b32 v205, v4, v5 offset0:152 offset1:220
	v_cvt_pk_bf16_f32 v4, v0, v1
	v_pk_fma_f32 v[0:1], v[214:215], v[0:1], v[2:3]
	v_lshlrev_b32_e32 v10, 16, v11
	v_pk_fma_f32 v[2:3], v[206:207], v[0:1], v[42:43] op_sel:[0,1,0] op_sel_hi:[1,0,1]
	v_and_b32_e32 v11, 0xffff0000, v11
	v_cvt_pk_bf16_f32 v5, v0, v1
	v_pk_fma_f32 v[0:1], v[214:215], v[0:1], v[2:3]
	v_lshlrev_b32_e32 v44, 16, v12
	v_pk_fma_f32 v[2:3], v[206:207], v[0:1], v[10:11] op_sel:[0,1,0] op_sel_hi:[1,0,1]
	v_and_b32_e32 v45, 0xffff0000, v12
	ds_write2_b32 v231, v4, v5 offset0:32 offset1:100
	v_cvt_pk_bf16_f32 v4, v0, v1
	v_pk_fma_f32 v[0:1], v[214:215], v[0:1], v[2:3]
	v_lshlrev_b32_e32 v12, 16, v13
	v_pk_fma_f32 v[2:3], v[206:207], v[0:1], v[44:45] op_sel:[0,1,0] op_sel_hi:[1,0,1]
	v_and_b32_e32 v13, 0xffff0000, v13
	v_cvt_pk_bf16_f32 v5, v0, v1
	v_pk_fma_f32 v[0:1], v[214:215], v[0:1], v[2:3]
	v_lshlrev_b32_e32 v46, 16, v14
	v_pk_fma_f32 v[2:3], v[206:207], v[0:1], v[12:13] op_sel:[0,1,0] op_sel_hi:[1,0,1]
	v_and_b32_e32 v47, 0xffff0000, v14
	ds_write2_b32 v231, v4, v5 offset0:168 offset1:236
	v_cvt_pk_bf16_f32 v4, v0, v1
	v_pk_fma_f32 v[0:1], v[214:215], v[0:1], v[2:3]
	v_lshlrev_b32_e32 v14, 16, v15
	v_pk_fma_f32 v[2:3], v[206:207], v[0:1], v[46:47] op_sel:[0,1,0] op_sel_hi:[1,0,1]
	v_and_b32_e32 v15, 0xffff0000, v15
	v_cvt_pk_bf16_f32 v5, v0, v1
	v_pk_fma_f32 v[0:1], v[214:215], v[0:1], v[2:3]
	v_lshlrev_b32_e32 v48, 16, v16
	v_pk_fma_f32 v[2:3], v[206:207], v[0:1], v[14:15] op_sel:[0,1,0] op_sel_hi:[1,0,1]
	v_and_b32_e32 v49, 0xffff0000, v16
	ds_write2_b32 v234, v4, v5 offset0:48 offset1:116
	v_cvt_pk_bf16_f32 v4, v0, v1
	v_pk_fma_f32 v[0:1], v[214:215], v[0:1], v[2:3]
	v_lshlrev_b32_e32 v16, 16, v17
	v_pk_fma_f32 v[2:3], v[206:207], v[0:1], v[48:49] op_sel:[0,1,0] op_sel_hi:[1,0,1]
	v_and_b32_e32 v17, 0xffff0000, v17
	v_cvt_pk_bf16_f32 v5, v0, v1
	v_pk_fma_f32 v[0:1], v[214:215], v[0:1], v[2:3]
	v_lshlrev_b32_e32 v50, 16, v18
	v_pk_fma_f32 v[2:3], v[206:207], v[0:1], v[16:17] op_sel:[0,1,0] op_sel_hi:[1,0,1]
	v_and_b32_e32 v51, 0xffff0000, v18
	ds_write2_b32 v234, v4, v5 offset0:184 offset1:252
	v_cvt_pk_bf16_f32 v4, v0, v1
	v_pk_fma_f32 v[0:1], v[214:215], v[0:1], v[2:3]
	v_lshlrev_b32_e32 v18, 16, v19
	v_pk_fma_f32 v[2:3], v[206:207], v[0:1], v[50:51] op_sel:[0,1,0] op_sel_hi:[1,0,1]
	v_and_b32_e32 v19, 0xffff0000, v19
	v_cvt_pk_bf16_f32 v5, v0, v1
	v_pk_fma_f32 v[0:1], v[214:215], v[0:1], v[2:3]
	ds_write2_b32 v235, v4, v5 offset0:64 offset1:132
	v_pk_fma_f32 v[2:3], v[206:207], v[0:1], v[18:19] op_sel:[0,1,0] op_sel_hi:[1,0,1]
	v_cvt_pk_bf16_f32 v4, v0, v1
	v_pk_fma_f32 v[0:1], v[214:215], v[0:1], v[2:3]
	ds_write2_b32 v221, v32, v33 offset1:68
	v_pk_fma_f32 v[2:3], v[206:207], v[0:1], v[52:53] op_sel:[0,1,0] op_sel_hi:[1,0,1]
	v_cvt_pk_bf16_f32 v5, v0, v1
	v_pk_fma_f32 v[0:1], v[214:215], v[0:1], v[2:3]
	ds_write2_b32 v236, v4, v5 offset0:72 offset1:140
	v_pk_fma_f32 v[2:3], v[212:213], v[0:1], v[54:55]
	v_cvt_pk_bf16_f32 v6, v0, v1
	v_pk_fma_f32 v[0:1], v[214:215], v[0:1], v[2:3] op_sel:[0,1,0] op_sel_hi:[1,0,1]
	v_or_b32_e32 v243, s12, v137
	v_pk_fma_f32 v[4:5], v[206:207], v[0:1], v[20:21]
	v_pk_mov_b32 v[2:3], v[0:1], v[0:1] op_sel:[1,0]
	v_pk_fma_f32 v[0:1], v[214:215], v[0:1], v[4:5] op_sel:[0,0,1] op_sel_hi:[1,1,0]
	v_cvt_pk_bf16_f32 v2, v2, v3
	v_pk_fma_f32 v[4:5], v[212:213], v[0:1], v[56:57] op_sel:[0,1,0] op_sel_hi:[1,0,1]
	ds_write2_b32 v237, v6, v2 offset0:80 offset1:148
	v_pk_mov_b32 v[2:3], v[0:1], v[0:1] op_sel:[1,0]
	v_pk_fma_f32 v[0:1], v[214:215], v[0:1], v[4:5]
	v_cvt_pk_bf16_f32 v6, v2, v3
	v_pk_fma_f32 v[4:5], v[212:213], v[0:1], v[22:23] op_sel:[0,1,0] op_sel_hi:[1,0,1]
	v_pk_mov_b32 v[2:3], v[0:1], v[0:1] op_sel:[1,0]
	v_pk_fma_f32 v[0:1], v[214:215], v[0:1], v[4:5]
	v_cvt_pk_bf16_f32 v2, v2, v3
	v_pk_fma_f32 v[4:5], v[212:213], v[0:1], v[58:59] op_sel:[0,1,0] op_sel_hi:[1,0,1]
	ds_write2_b32 v238, v6, v2 offset0:88 offset1:156
	v_pk_mov_b32 v[2:3], v[0:1], v[0:1] op_sel:[1,0]
	v_pk_fma_f32 v[0:1], v[214:215], v[0:1], v[4:5]
	v_cvt_pk_bf16_f32 v6, v2, v3
	v_pk_fma_f32 v[4:5], v[212:213], v[0:1], v[24:25] op_sel:[0,1,0] op_sel_hi:[1,0,1]
	v_pk_mov_b32 v[2:3], v[0:1], v[0:1] op_sel:[1,0]
	v_pk_fma_f32 v[0:1], v[214:215], v[0:1], v[4:5]
	v_cvt_pk_bf16_f32 v2, v2, v3
	v_pk_fma_f32 v[4:5], v[212:213], v[0:1], v[60:61] op_sel:[0,1,0] op_sel_hi:[1,0,1]
	ds_write2_b32 v239, v6, v2 offset0:96 offset1:164
	v_pk_mov_b32 v[2:3], v[0:1], v[0:1] op_sel:[1,0]
	v_pk_fma_f32 v[0:1], v[214:215], v[0:1], v[4:5]
	v_cvt_pk_bf16_f32 v6, v2, v3
	v_pk_fma_f32 v[4:5], v[212:213], v[0:1], v[26:27] op_sel:[0,1,0] op_sel_hi:[1,0,1]
	v_pk_mov_b32 v[2:3], v[0:1], v[0:1] op_sel:[1,0]
	v_pk_fma_f32 v[0:1], v[214:215], v[0:1], v[4:5]
	v_cvt_pk_bf16_f32 v2, v2, v3
	v_pk_fma_f32 v[4:5], v[212:213], v[0:1], v[62:63] op_sel:[0,1,0] op_sel_hi:[1,0,1]
	ds_write2_b32 v240, v6, v2 offset0:104 offset1:172
	v_pk_mov_b32 v[2:3], v[0:1], v[0:1] op_sel:[1,0]
	v_pk_fma_f32 v[0:1], v[214:215], v[0:1], v[4:5]
	v_cvt_pk_bf16_f32 v6, v2, v3
	v_pk_fma_f32 v[4:5], v[212:213], v[0:1], v[28:29] op_sel:[0,1,0] op_sel_hi:[1,0,1]
	v_pk_mov_b32 v[2:3], v[0:1], v[0:1] op_sel:[1,0]
	v_pk_fma_f32 v[0:1], v[214:215], v[0:1], v[4:5]
	v_cvt_pk_bf16_f32 v2, v2, v3
	v_pk_fma_f32 v[4:5], v[212:213], v[0:1], v[232:233] op_sel:[0,1,0] op_sel_hi:[1,0,1]
	ds_write2_b32 v241, v6, v2 offset0:112 offset1:180
	v_pk_fma_f32 v[216:217], v[214:215], v[0:1], v[4:5]
	v_pk_mov_b32 v[2:3], v[0:1], v[0:1] op_sel:[1,0]
	v_pk_mov_b32 v[0:1], v[216:217], v[216:217] op_sel:[1,0]
	v_cvt_pk_bf16_f32 v2, v2, v3
	v_cvt_pk_bf16_f32 v0, v0, v1
	ds_write2_b32 v242, v2, v0 offset0:120 offset1:188
	s_waitcnt lgkmcnt(0)
	ds_read_b128 v[0:3], v222
	ds_read_b128 v[4:7], v222 offset:64
	s_waitcnt lgkmcnt(1)
	v_mfma_f32_16x16x32_bf16 v[0:3], v[80:83], v[0:3], 0
	v_mad_u32_u24 v18, v243, s17, v203
	ds_read_b64 v[12:13], v18
	ds_read_b128 v[8:11], v222 offset:128
	v_mov_b64_e32 v[218:219], s[20:21]
	s_waitcnt lgkmcnt(2)
	v_mfma_f32_16x16x32_bf16 v[0:3], v[84:87], v[4:7], v[0:3]
	ds_read_b128 v[4:7], v222 offset:192
	ds_read_b64 v[14:15], v18 offset:16640
	s_waitcnt lgkmcnt(3)
	v_lshlrev_b32_e32 v16, 16, v12
	v_and_b32_e32 v17, 0xffff0000, v12
	s_waitcnt lgkmcnt(2)
	v_mfma_f32_16x16x32_bf16 v[0:3], v[88:91], v[8:11], v[0:3]
	v_lshlrev_b32_e32 v8, 16, v13
	v_and_b32_e32 v9, 0xffff0000, v13
	s_mov_b32 s12, 32
	s_waitcnt lgkmcnt(1)
	v_mfma_f32_16x16x32_bf16 v[0:3], v[92:95], v[4:7], v[0:3]
	s_nop 7
	v_pk_fma_f32 v[0:1], v[96:97], v[16:17], v[0:1]
	v_pk_fma_f32 v[2:3], v[98:99], v[8:9], v[2:3]
	v_and_b32_e32 v5, 0x7fffffff, v1
	v_and_b32_e32 v4, 0x7fffffff, v0
	v_and_b32_e32 v9, 0x7fffffff, v3
	v_and_b32_e32 v8, 0x7fffffff, v2
	v_pk_fma_f32 v[4:5], v[4:5], s[16:17], 1.0 op_sel_hi:[1,0,0]
	v_pk_fma_f32 v[8:9], v[8:9], s[16:17], 1.0 op_sel_hi:[1,0,0]
	v_rcp_f32_e32 v4, v4
	v_rcp_f32_e32 v5, v5
	v_rcp_f32_e32 v8, v8
	v_rcp_f32_e32 v9, v9
	v_pk_mul_f32 v[6:7], v[0:1], v[0:1]
	v_pk_mul_f32 v[10:11], v[2:3], v[2:3]
	v_pk_mul_f32 v[6:7], v[6:7], s[28:29] op_sel_hi:[1,0]
	v_pk_mul_f32 v[10:11], v[10:11], s[28:29] op_sel_hi:[1,0]
	v_pk_fma_f32 v[12:13], v[4:5], s[18:19], v[218:219] op_sel_hi:[1,0,0]
	v_pk_fma_f32 v[16:17], v[8:9], s[18:19], v[218:219] op_sel_hi:[1,0,0]
	v_exp_f32_e32 v6, v6
	v_exp_f32_e32 v7, v7
	v_exp_f32_e32 v10, v10
	v_exp_f32_e32 v11, v11
	v_pk_fma_f32 v[12:13], v[4:5], v[12:13], s[22:23] op_sel_hi:[1,1,0]
	v_pk_fma_f32 v[16:17], v[8:9], v[16:17], s[22:23] op_sel_hi:[1,1,0]
	v_pk_fma_f32 v[12:13], v[4:5], v[12:13], s[24:25] op_sel_hi:[1,1,0]
	v_pk_fma_f32 v[16:17], v[8:9], v[16:17], s[24:25] op_sel_hi:[1,1,0]
	v_pk_fma_f32 v[12:13], v[4:5], v[12:13], s[26:27] op_sel_hi:[1,1,0]
	v_pk_fma_f32 v[16:17], v[8:9], v[16:17], s[26:27] op_sel_hi:[1,1,0]
	v_pk_mul_f32 v[4:5], v[4:5], v[12:13]
	v_pk_mul_f32 v[8:9], v[8:9], v[16:17]
	v_pk_mul_f32 v[4:5], v[6:7], v[4:5]
	v_pk_mul_f32 v[6:7], v[10:11], v[8:9]
	v_pk_mul_f32 v[8:9], v[0:1], v[4:5]
	v_pk_fma_f32 v[4:5], v[0:1], v[4:5], v[0:1] neg_lo:[1,0,0] neg_hi:[1,0,0]
	v_cmp_gt_f32_e32 vcc, 0, v0
	v_pk_mul_f32 v[10:11], v[2:3], v[6:7]
	v_pk_fma_f32 v[6:7], v[2:3], v[6:7], v[2:3] neg_lo:[1,0,0] neg_hi:[1,0,0]
	v_cmp_gt_f32_e64 s[4:5], 0, v2
	v_cmp_gt_f32_e64 s[6:7], 0, v3
	v_cmp_gt_f32_e64 s[8:9], 0, v1
	v_cndmask_b32_e32 v1, v4, v8, vcc
	v_cndmask_b32_e64 v2, v7, v11, s[6:7]
	v_cndmask_b32_e64 v0, v5, v9, s[8:9]
	v_cndmask_b32_e64 v3, v6, v10, s[4:5]
	v_cvt_pk_bf16_f32 v0, v1, v0
	v_cvt_pk_bf16_f32 v1, v3, v2
	ds_write_b64 v18, v[0:1]
	ds_read_b128 v[0:3], v222 offset:4352
	ds_read_b128 v[4:7], v222 offset:4416
	s_waitcnt lgkmcnt(1)
	v_mfma_f32_16x16x32_bf16 v[0:3], v[80:83], v[0:3], 0
	v_lshlrev_b32_e32 v12, 16, v14
	v_and_b32_e32 v13, 0xffff0000, v14
	s_waitcnt lgkmcnt(0)
	v_mfma_f32_16x16x32_bf16 v[0:3], v[84:87], v[4:7], v[0:3]
	ds_read_b128 v[4:7], v222 offset:4480
	ds_read_b128 v[8:11], v222 offset:4544
	s_waitcnt lgkmcnt(1)
	v_mfma_f32_16x16x32_bf16 v[0:3], v[88:91], v[4:7], v[0:3]
	v_lshlrev_b32_e32 v4, 16, v15
	v_and_b32_e32 v5, 0xffff0000, v15
	s_waitcnt lgkmcnt(0)
	v_mfma_f32_16x16x32_bf16 v[0:3], v[92:95], v[8:11], v[0:3]
	s_nop 7
	v_pk_fma_f32 v[0:1], v[96:97], v[12:13], v[0:1]
	v_pk_fma_f32 v[2:3], v[98:99], v[4:5], v[2:3]
	v_and_b32_e32 v5, 0x7fffffff, v1
	v_and_b32_e32 v4, 0x7fffffff, v0
	v_and_b32_e32 v9, 0x7fffffff, v3
	v_and_b32_e32 v8, 0x7fffffff, v2
	v_pk_fma_f32 v[4:5], v[4:5], s[16:17], 1.0 op_sel_hi:[1,0,0]
	v_pk_fma_f32 v[8:9], v[8:9], s[16:17], 1.0 op_sel_hi:[1,0,0]
	v_rcp_f32_e32 v4, v4
	v_rcp_f32_e32 v5, v5
	v_rcp_f32_e32 v8, v8
	v_rcp_f32_e32 v9, v9
	v_pk_mul_f32 v[6:7], v[0:1], v[0:1]
	v_pk_mul_f32 v[10:11], v[2:3], v[2:3]
	v_pk_mul_f32 v[6:7], v[6:7], s[28:29] op_sel_hi:[1,0]
	v_pk_mul_f32 v[10:11], v[10:11], s[28:29] op_sel_hi:[1,0]
	v_pk_fma_f32 v[12:13], v[4:5], s[18:19], v[218:219] op_sel_hi:[1,0,0]
	v_pk_fma_f32 v[14:15], v[8:9], s[18:19], v[218:219] op_sel_hi:[1,0,0]
	v_exp_f32_e32 v6, v6
	v_exp_f32_e32 v7, v7
	v_exp_f32_e32 v10, v10
	v_exp_f32_e32 v11, v11
	v_pk_fma_f32 v[12:13], v[4:5], v[12:13], s[22:23] op_sel_hi:[1,1,0]
	v_pk_fma_f32 v[14:15], v[8:9], v[14:15], s[22:23] op_sel_hi:[1,1,0]
	v_pk_fma_f32 v[12:13], v[4:5], v[12:13], s[24:25] op_sel_hi:[1,1,0]
	v_pk_fma_f32 v[14:15], v[8:9], v[14:15], s[24:25] op_sel_hi:[1,1,0]
	v_pk_fma_f32 v[12:13], v[4:5], v[12:13], s[26:27] op_sel_hi:[1,1,0]
	v_pk_fma_f32 v[14:15], v[8:9], v[14:15], s[26:27] op_sel_hi:[1,1,0]
	v_pk_mul_f32 v[4:5], v[4:5], v[12:13]
	v_pk_mul_f32 v[8:9], v[8:9], v[14:15]
	v_pk_mul_f32 v[4:5], v[6:7], v[4:5]
	v_pk_mul_f32 v[6:7], v[10:11], v[8:9]
	v_pk_mul_f32 v[8:9], v[0:1], v[4:5]
	v_pk_fma_f32 v[4:5], v[0:1], v[4:5], v[0:1] neg_lo:[1,0,0] neg_hi:[1,0,0]
	v_cmp_gt_f32_e32 vcc, 0, v0
	v_pk_mul_f32 v[10:11], v[2:3], v[6:7]
	v_pk_fma_f32 v[6:7], v[2:3], v[6:7], v[2:3] neg_lo:[1,0,0] neg_hi:[1,0,0]
	v_cmp_gt_f32_e64 s[4:5], 0, v2
	v_cmp_gt_f32_e64 s[6:7], 0, v3
	v_cmp_gt_f32_e64 s[8:9], 0, v1
	v_cndmask_b32_e32 v1, v4, v8, vcc
	v_cndmask_b32_e64 v2, v7, v11, s[6:7]
	v_cndmask_b32_e64 v0, v5, v9, s[8:9]
	v_cndmask_b32_e64 v3, v6, v10, s[4:5]
	v_cvt_pk_bf16_f32 v0, v1, v0
	v_cvt_pk_bf16_f32 v1, v3, v2
	ds_write_b64 v18, v[0:1] offset:16640
	s_waitcnt lgkmcnt(0)
	s_andn2_b64 vcc, exec, s[48:49]
	s_mov_b64 s[48:49], 0
	s_cbranch_vccz .LBB0_456
	s_add_i32 s39, s39, 1
	s_waitcnt vmcnt(3)
	v_mov_b64_e32 v[80:81], v[116:117]
	s_waitcnt vmcnt(2)
	v_mov_b64_e32 v[84:85], v[120:121]
	s_waitcnt vmcnt(1)
	v_mov_b64_e32 v[88:89], v[128:129]
	s_waitcnt vmcnt(0)
	v_mov_b64_e32 v[92:93], v[132:133]
	v_mov_b64_e32 v[64:65], v[100:101]
	v_mov_b64_e32 v[68:69], v[104:105]
	v_mov_b64_e32 v[72:73], v[108:109]
	v_mov_b64_e32 v[76:77], v[112:113]
	v_mov_b64_e32 v[96:97], v[124:125]
	s_cmp_eq_u32 s39, 4
	v_mov_b64_e32 v[82:83], v[118:119]
	v_mov_b64_e32 v[86:87], v[122:123]
	v_mov_b64_e32 v[90:91], v[130:131]
	v_mov_b64_e32 v[94:95], v[134:135]
	v_mov_b64_e32 v[66:67], v[102:103]
	v_mov_b64_e32 v[70:71], v[106:107]
	v_mov_b64_e32 v[74:75], v[110:111]
	v_mov_b64_e32 v[78:79], v[114:115]
	v_mov_b64_e32 v[206:207], v[210:211]
	v_mov_b64_e32 v[0:1], v[208:209]
	v_mov_b64_e32 v[98:99], v[126:127]
	s_cbranch_scc0 .LBB0_453
	s_waitcnt lgkmcnt(0)
	global_load_dwordx4 v[64:67], v[168:169], off
	global_load_dwordx4 v[68:71], v[168:169], off offset:1024
	global_load_dwordx4 v[72:75], v[170:171], off
	global_load_dwordx4 v[76:79], v[172:173], off
	global_load_dwordx4 v[80:83], v[168:169], off offset:2048
	global_load_dwordx4 v[84:87], v[168:169], off offset:3072
	global_load_dwordx4 v[88:91], v[174:175], off
	global_load_dwordx4 v[92:95], v[176:177], off
	s_barrier
	v_mov_b32_e32 v0, 0
	s_mov_b32 s6, 0
	v_mov_b32_e32 v130, v195
	v_mov_b32_e32 v131, v191
	v_mov_b64_e32 v[128:129], v[200:201]
	v_mov_b32_e32 v1, v0
	v_mov_b32_e32 v2, v0
	v_mov_b32_e32 v3, v0
	v_mov_b32_e32 v4, v0
	v_mov_b32_e32 v5, v0
	v_mov_b32_e32 v6, v0
	v_mov_b32_e32 v7, v0
	v_mov_b32_e32 v8, v0
	v_mov_b32_e32 v9, v0
	v_mov_b32_e32 v10, v0
	v_mov_b32_e32 v11, v0
	v_mov_b32_e32 v12, v0
	v_mov_b32_e32 v13, v0
	v_mov_b32_e32 v14, v0
	v_mov_b32_e32 v15, v0
	v_mov_b32_e32 v32, v0
	v_mov_b32_e32 v33, v0
	v_mov_b32_e32 v34, v0
	v_mov_b32_e32 v35, v0
	v_mov_b32_e32 v36, v0
	v_mov_b32_e32 v37, v0
	v_mov_b32_e32 v38, v0
	v_mov_b32_e32 v39, v0
	v_mov_b32_e32 v40, v0
	v_mov_b32_e32 v41, v0
	v_mov_b32_e32 v42, v0
	v_mov_b32_e32 v43, v0
	v_mov_b32_e32 v44, v0
	v_mov_b32_e32 v45, v0
	v_mov_b32_e32 v46, v0
	v_mov_b32_e32 v47, v0
	v_mov_b32_e32 v16, v0
	v_mov_b32_e32 v17, v0
	v_mov_b32_e32 v18, v0
	v_mov_b32_e32 v19, v0
	v_mov_b32_e32 v20, v0
	v_mov_b32_e32 v21, v0
	v_mov_b32_e32 v22, v0
	v_mov_b32_e32 v23, v0
	v_mov_b32_e32 v24, v0
	v_mov_b32_e32 v25, v0
	v_mov_b32_e32 v26, v0
	v_mov_b32_e32 v27, v0
	v_mov_b32_e32 v28, v0
	v_mov_b32_e32 v29, v0
	v_mov_b32_e32 v30, v0
	v_mov_b32_e32 v31, v0
	v_mov_b32_e32 v48, v0
	v_mov_b32_e32 v49, v0
	v_mov_b32_e32 v50, v0
	v_mov_b32_e32 v51, v0
	v_mov_b32_e32 v52, v0
	v_mov_b32_e32 v53, v0
	v_mov_b32_e32 v54, v0
	v_mov_b32_e32 v55, v0
	v_mov_b32_e32 v56, v0
	v_mov_b32_e32 v57, v0
	v_mov_b32_e32 v58, v0
	v_mov_b32_e32 v59, v0
	v_mov_b32_e32 v60, v0
	v_mov_b32_e32 v61, v0
	v_mov_b32_e32 v62, v0
	v_mov_b32_e32 v63, v0
	s_branch .LBB0_460

.LBB0_460:
	v_add_co_u32_e32 v96, vcc, s23, v128
	v_add_u32_e32 v132, v130, v140
	s_nop 0
	v_addc_co_u32_e32 v97, vcc, -1, v129, vcc
	global_load_dwordx4 v[124:127], v[96:97], off offset:-4096
	global_load_dwordx4 v[116:119], v[96:97], off offset:-3072
	global_load_dwordx4 v[120:123], v[128:129], off offset:-4096
	global_load_dwordx4 v[112:115], v[128:129], off offset:-3072
	global_load_dwordx4 v[108:111], v[96:97], off offset:-2048
	global_load_dwordx4 v[100:103], v[96:97], off offset:-1024
	global_load_dwordx4 v[104:107], v[128:129], off offset:-2048
	s_nop 0
	global_load_dwordx4 v[96:99], v[128:129], off offset:-1024
	v_add_u32_e32 v133, 0x11000, v132
	ds_read_b128 v[206:209], v133
	v_add_u32_e32 v133, v131, v140
	v_add_u32_e32 v134, 0x11000, v133
	ds_read_b128 v[210:213], v134
	s_waitcnt vmcnt(15) lgkmcnt(1)
	v_mfma_f32_32x32x16_bf16 v[48:63], v[64:67], v[206:209], v[48:63]
	v_add_u32_e32 v134, 0x11020, v132
	s_cmp_gt_u32 s6, 5
	s_cselect_b64 s[4:5], -1, 0
	s_cmp_lt_u32 s6, 6
	s_waitcnt lgkmcnt(0)
	v_mfma_f32_32x32x16_bf16 v[16:31], v[64:67], v[210:213], v[16:31]
	s_waitcnt vmcnt(13)
	v_mfma_f32_32x32x16_bf16 v[32:47], v[72:75], v[206:209], v[32:47]
	ds_read_b128 v[206:209], v134
	v_add_u32_e32 v134, 0x11020, v133
	v_mfma_f32_32x32x16_bf16 v[0:15], v[72:75], v[210:213], v[0:15]
	ds_read_b128 v[210:213], v134
	v_add_u32_e32 v134, 0x11040, v132
	s_waitcnt lgkmcnt(1)
	v_mfma_f32_32x32x16_bf16 v[48:63], v[68:71], v[206:209], v[48:63]
	s_waitcnt lgkmcnt(0)
	v_mfma_f32_32x32x16_bf16 v[16:31], v[68:71], v[210:213], v[16:31]
	s_waitcnt vmcnt(12)
	v_mfma_f32_32x32x16_bf16 v[32:47], v[76:79], v[206:209], v[32:47]
	ds_read_b128 v[206:209], v134
	v_add_u32_e32 v134, 0x11040, v133
	v_mfma_f32_32x32x16_bf16 v[0:15], v[76:79], v[210:213], v[0:15]
	ds_read_b128 v[210:213], v134
	v_add_u32_e32 v134, 0x11060, v132
	s_waitcnt vmcnt(11) lgkmcnt(1)
	v_mfma_f32_32x32x16_bf16 v[48:63], v[80:83], v[206:209], v[48:63]
	s_waitcnt lgkmcnt(0)
	v_mfma_f32_32x32x16_bf16 v[16:31], v[80:83], v[210:213], v[16:31]
	s_waitcnt vmcnt(9)
	v_mfma_f32_32x32x16_bf16 v[32:47], v[88:91], v[206:209], v[32:47]
	ds_read_b128 v[206:209], v134
	v_add_u32_e32 v134, 0x11060, v133
	v_mfma_f32_32x32x16_bf16 v[0:15], v[88:91], v[210:213], v[0:15]
	ds_read_b128 v[210:213], v134
	s_waitcnt lgkmcnt(1)
	v_mfma_f32_32x32x16_bf16 v[48:63], v[84:87], v[206:209], v[48:63]
	s_waitcnt lgkmcnt(0)
	v_mfma_f32_32x32x16_bf16 v[16:31], v[84:87], v[210:213], v[16:31]
	s_waitcnt vmcnt(8)
	v_mfma_f32_32x32x16_bf16 v[32:47], v[92:95], v[206:209], v[32:47]
	v_mfma_f32_32x32x16_bf16 v[0:15], v[92:95], v[210:213], v[0:15]
	s_cbranch_scc0 .LBB0_459
	v_add_co_u32_e32 v84, vcc, 0xffff8000, v128
	s_nop 1
	v_addc_co_u32_e32 v85, vcc, -1, v129, vcc
	global_load_dwordx4 v[64:67], v[84:85], off
	global_load_dwordx4 v[68:71], v[84:85], off offset:1024
	global_load_dwordx4 v[72:75], v[128:129], off
	global_load_dwordx4 v[76:79], v[128:129], off offset:1024
	global_load_dwordx4 v[80:83], v[84:85], off offset:2048
	s_nop 0
	global_load_dwordx4 v[84:87], v[84:85], off offset:3072
	s_nop 0
	global_load_dwordx4 v[88:91], v[128:129], off offset:2048
	global_load_dwordx4 v[92:95], v[128:129], off offset:3072
	s_branch .Lglu_mma1_steady
